# v20 + P5 K-loop LDS-DMA issue evened out 2/6/2/6 -> 4/4/4/4 (A pieces staged one phase later, vmcnt 8/6/8/6), run 1
# speedup vs baseline: 1.0026x; 1.0026x over previous
; #define PG8_STAGE(bufoff, gbase, voff) do { _Pragma("unroll") for (int _i = 0; _i < 2; ++_i) \
;         __builtin_amdgcn_global_load_lds((const unsigned*)((const char*)(gbase) + (voff)[_i]), (LAS unsigned*)(lds + (bufoff) + ldsw + _i * 8192), 16, 0, 0); } while (0)
; #define PG8_WAIT_V(n) asm volatile("s_waitcnt vmcnt(" #n ")" ::: "memory")
; #define PG8_BAR __builtin_amdgcn_s_barrier()
; template <class Epi, bool ALIGN_EPI, bool SPLITA>
; __device__ __forceinline__ void gemm_phase(LAS unsigned char* lds, const Gemm g, const StaticOrder& S, const Epi& E) {
;     ...
;     { const unsigned vo[2] = {mirC ? voffAm[0] : voffA[0], mirC ? voffAm[1] : voffA[1]}; const char* cAh = mirC ? cA - hstepA : cA + hstepA;
;       PG8_STAGE(PG8_SB(0, 0), cB, voffB); PG8_STAGE(PG8_SB(0, 1), cB + hstepB, voffB); PG8_STAGE(PG8_SA(0, 0), cA, vo); PG8_STAGE(PG8_SA(0, 1), cAh, vo);
;       if (wr == 1) PG8_BAR;
;       PG8_WAIT_V(2); PG8_BAR;
;       PG8_STAGE(PG8_SB(1, 0), cB + kstepB, voffB); PG8_STAGE(PG8_SA(1, 0), cA + kofs(1), vo); PG8_STAGE(PG8_SB(1, 1), cB + hstepB + kstepB, voffB); }
;     PG8_WAIT_V(6); PG8_BAR;
.LBB0_790:
	s_and_b32 s48, s8, 3
	s_mov_b64 s[8:9], 0x800
	s_add_i32 m0, s42, 0x18000
	v_lshl_add_u64 v[8:9], v[8:9], 0, s[8:9]
	s_ashr_i32 s47, s15, 31
	s_lshl_b32 s17, s3, 13
	s_lshl_b32 s18, s48, 12
	s_waitcnt vmcnt(2)
	s_barrier
	global_load_lds_dwordx4 v[8:9], off
	v_lshl_add_u64 v[6:7], v[6:7], 0, s[8:9]
	s_add_i32 m0, s42, 0x1a000
	s_mov_b64 s[10:11], 0x80
	s_add_i32 s49, s42, 0x8000
	s_add_i32 s50, s42, 0xa000
	global_load_lds_dwordx4 v[6:7], off
	s_add_u32 s12, s36, 0x40800
	s_addc_u32 s13, s37, 0
	s_add_i32 m0, s42, 0x1c000
	v_lshl_add_u64 v[2:3], s[12:13], 0, v[134:135]
	global_load_lds_dwordx4 v[2:3], off
	v_lshl_add_u64 v[2:3], s[12:13], 0, v[130:131]
	s_add_i32 m0, s42, 0x1e000
	v_lshlrev_b32_e32 v5, 2, v12
	global_load_lds_dwordx4 v[2:3], off
	v_lshrrev_b32_e32 v2, 1, v12
	v_and_b32_e32 v2, 24, v2
	v_and_b32_e32 v3, 15, v12
	v_lshlrev_b32_e32 v4, 1, v2
	v_lshl_or_b32 v4, v3, 6, v4
	v_and_b32_e32 v5, 32, v5
	v_lshl_or_b32 v1, s3, 6, v3
	v_bitop3_b32 v6, v4, s17, v5 bitop3:0xde
	v_bitop3_b32 v154, v4, s18, v5 bitop3:0xde
	v_lshlrev_b32_e32 v4, 5, v3
	v_lshlrev_b32_e32 v3, 14, v15
	v_and_b32_e32 v3, 0xffff8000, v3
	v_lshl_add_u32 v3, v14, 11, v3
	v_and_b32_e32 v5, 1, v15
	s_cmpk_lt_u32 s16, 0x100
	v_lshl_or_b32 v3, v5, 6, v3
	s_sext_i32_i8 s30, s2
	s_cselect_b64 s[16:17], -1, 0
	s_lshl_b32 s2, s3, 5
	v_lshl_add_u32 v140, v16, 1, v3
	v_lshlrev_b32_e32 v3, 14, v10
	s_and_b32 s2, s2, 0x60
	v_and_b32_e32 v3, 0xffff8000, v3
	s_waitcnt vmcnt(4)
	s_or_b32 s2, s2, s48
	v_lshl_add_u32 v3, v11, 11, v3
	v_and_b32_e32 v5, 1, v10
	s_lshl_b32 s2, s2, 9
	v_lshl_or_b32 v3, v5, 6, v3
	s_add_i32 s51, 0, 0x10000
	s_add_i32 s52, 0, 0x14000
	v_mov_b32_e32 v141, v139
	v_lshl_add_u32 v142, v13, 1, v3
	v_mov_b32_e32 v143, v139
	v_mov_b64_e32 v[144:145], 0xc00
	v_mov_b64_e32 v[146:147], 0xbff
	v_add_u32_e32 v155, s51, v154
	v_add_u32_e32 v156, s52, v154
	v_add_u32_e32 v157, 0, v6
	v_mov_b32_e32 v158, 0x358637bd
	s_lshl_b32 s53, s2, 1
	v_lshlrev_b32_e32 v138, 1, v4
	v_lshlrev_b32_e32 v148, 1, v2
	s_movk_i32 s54, 0x1000
	s_barrier
	s_branch .LBB0_793

; #define PG8_WAIT_V(n) asm volatile("s_waitcnt vmcnt(" #n ")" ::: "memory")
; #define PG8_BAR __builtin_amdgcn_s_barrier()
; template <class Epi, bool ALIGN_EPI, bool SPLITA>
; __device__ __forceinline__ void gemm_phase(LAS unsigned char* lds, const Gemm g, const StaticOrder& S, const Epi& E) {
;     ...
;         const bool has_next = S.next(ui + 1, nxt);
;         const char* nA = has_next ? baseA1(nxt) : cA;
;         const char* nB = has_next ? baseB(nxt) : cB;
;         const bool mirN = has_next ? mirrored(nxt) : mirC;
;         for (int t = 0; t < nt; t += 2) {
;             const bool last = (t == nt - 2);
;             if constexpr (Epi::MIDK) { if (t == g.ksplit) E.mid(acc, cur, wr, wc, fr, fq); }
;             const char *a1, *a2;
;             if constexpr (SPLITA) {
;                 a1 = (t + 1 < g.ksplit) ? cA + (size_t)(t + 1) * kstep : cA2 + (size_t)(t + 1 - g.ksplit) * 2048;
;                 a2 = last ? nA : ((t + 2 < g.ksplit) ? cA + (size_t)(t + 2) * kstep : cA2 + (size_t)(t + 2 - g.ksplit) * 2048);
;             } else { a1 = cA + kofs(t + 1); a2 = last ? nA : cA + kofs(t + 2); }
;             const char* b2 = last ? nB : cB + (size_t)(t + 2) * kstepB;
;             const bool s2a = SPLITA && (t + 1 >= g.ksplit), s2b = SPLITA && !last && (t + 2 >= g.ksplit);
;             const char* a3 = a2 + ((Epi::KSUB || s2b) ? (size_t)2048 : kstep); const char* b3 = b2 + kstepB;
;             const bool m1 = SPLITA && mirC && (t + 1 < g.ksplit), m2 = SPLITA && (last ? mirN : (mirC && (t + 2 < g.ksplit)));
;             const unsigned vo1[2] = {s2a ? voffA2[0] : m1 ? voffAm[0] : voffA[0], s2a ? voffA2[1] : m1 ? voffAm[1] : voffA[1]}, vo2[2] = {s2b ? voffA2[0] : m2 ? voffAm[0] : voffA[0], s2b ? voffA2[1] : m2 ? voffAm[1] : voffA[1]};
;             const char* a1h = m1 ? a1 - hstepA : a1 + hstepA; const char* a2h = m2 ? a2 - hstepA : a2 + hstepA;
;             PG8_LDB(B0, 0, 0); PG8_LDB(B1, 0, 1); PG8_SCHED; PG8_LDA(At, 0, 0); PG8_STAGE(PG8_SA(1, 1), a1h, vo1);
;             PG8_WAIT_V(8); PG8_WAIT_L(0); PG8_BAR; PG8_MMA(0, 0, At, B0); PG8_MMA(0, 1, At, B1); PG8_BAR; PG8_SCHED;
;             PG8_LDA(At, 0, 1); PG8_STAGE(PG8_SB(0, 0), b2, voffB); PG8_STAGE(PG8_SB(0, 1), b2 + hstepB, voffB); PG8_STAGE(PG8_SA(0, 0), a2, vo2);
;             PG8_WAIT_V(8); PG8_WAIT_L(0); PG8_BAR; PG8_MMA(1, 0, At, B0); PG8_MMA(1, 1, At, B1); PG8_BAR; PG8_SCHED;
.LBB0_795:
	s_ashr_i32 s19, s18, 31
	s_lshl_b64 s[12:13], s[18:19], 19
	s_add_u32 s22, s34, s12
	s_addc_u32 s23, s35, s13
	s_and_b64 s[12:13], s[2:3], exec
	s_cselect_b32 s19, s23, s39
	s_cselect_b32 s29, s22, s38
	s_ashr_i32 s21, s20, 31
	s_lshl_b64 s[12:13], s[20:21], 19
	s_add_u32 s24, s26, s12
	s_addc_u32 s25, s27, s13
	s_and_b64 s[12:13], s[2:3], exec
	s_cselect_b32 s21, s25, s37
	s_cselect_b32 s31, s24, s36
	s_add_u32 s55, s36, 0x1000
	s_addc_u32 s56, s37, 0
	s_add_u32 s36, s38, 0x40080
	s_addc_u32 s37, s39, 0
	s_mov_b32 s57, -2
	ds_read_b128 v[150:153], v155
	ds_read_b128 v[160:163], v155 offset:1024
	ds_read_b128 v[164:167], v155 offset:2048
	ds_read_b128 v[168:171], v155 offset:3072
	ds_read_b128 v[172:175], v156
	ds_read_b128 v[176:179], v156 offset:1024
	ds_read_b128 v[180:183], v156 offset:2048
	ds_read_b128 v[184:187], v156 offset:3072
	s_add_u32 s98, s36, 0xfffc0000
	s_addc_u32 s99, s37, -1
	s_add_u32 s12, s36, 0xfffc0080
	s_addc_u32 s13, s37, -1
	s_cmp_eq_u32 s57, 12
	s_cselect_b32 s41, s19, s13
	s_cselect_b32 s40, s29, s12
	s_cselect_b32 s39, s21, s56
	s_cselect_b32 s38, s31, s55
	s_mov_b32 m0, s49
	ds_read_b128 v[188:191], v157
	ds_read_b128 v[192:195], v157 offset:1024
	ds_read_b128 v[196:199], v157 offset:2048
	ds_read_b128 v[200:203], v157 offset:3072
	ds_read_b128 v[204:207], v157 offset:4096
	ds_read_b128 v[208:211], v157 offset:5120
	ds_read_b128 v[212:215], v157 offset:6144
	ds_read_b128 v[216:219], v157 offset:7168
	global_load_lds_dwordx4 v136, s[98:99]
	s_mov_b32 m0, s50
	s_nop 0
	global_load_lds_dwordx4 v132, s[98:99]
	s_add_i32 m0, s42, 0xc000
	s_nop 0
	global_load_lds_dwordx4 v140, s[36:37]
	s_add_i32 m0, s42, 0xe000
	s_nop 0
	global_load_lds_dwordx4 v142, s[36:37]
	s_waitcnt vmcnt(8)
	s_waitcnt lgkmcnt(0)
	s_barrier
	s_setprio 1
	s_waitcnt lgkmcnt(0)
	v_mfma_f32_16x16x32_bf16 v[126:129], v[150:153], v[188:191], 0
	v_mfma_f32_16x16x32_bf16 v[122:125], v[164:167], v[188:191], 0
	v_mfma_f32_16x16x32_bf16 v[110:113], v[150:153], v[196:199], 0
	v_mfma_f32_16x16x32_bf16 v[106:109], v[164:167], v[196:199], 0
	v_mfma_f32_16x16x32_bf16 v[94:97], v[150:153], v[204:207], 0
	v_mfma_f32_16x16x32_bf16 v[90:93], v[164:167], v[204:207], 0
	v_mfma_f32_16x16x32_bf16 v[78:81], v[150:153], v[212:215], 0
	v_mfma_f32_16x16x32_bf16 v[74:77], v[164:167], v[212:215], 0
	v_mfma_f32_16x16x32_bf16 v[126:129], v[160:163], v[192:195], v[126:129]
	v_mfma_f32_16x16x32_bf16 v[122:125], v[168:171], v[192:195], v[122:125]
	v_mfma_f32_16x16x32_bf16 v[110:113], v[160:163], v[200:203], v[110:113]
	v_mfma_f32_16x16x32_bf16 v[106:109], v[168:171], v[200:203], v[106:109]
	v_mfma_f32_16x16x32_bf16 v[94:97], v[160:163], v[208:211], v[94:97]
	v_mfma_f32_16x16x32_bf16 v[90:93], v[168:171], v[208:211], v[90:93]
	v_mfma_f32_16x16x32_bf16 v[78:81], v[160:163], v[216:219], v[78:81]
	v_mfma_f32_16x16x32_bf16 v[74:77], v[168:171], v[216:219], v[74:77]
	s_setprio 0
	s_setprio 1
	v_mfma_f32_16x16x32_bf16 v[118:121], v[172:175], v[188:191], 0
	v_mfma_f32_16x16x32_bf16 v[114:117], v[180:183], v[188:191], 0
	v_mfma_f32_16x16x32_bf16 v[102:105], v[172:175], v[196:199], 0
	v_mfma_f32_16x16x32_bf16 v[98:101], v[180:183], v[196:199], 0
	v_mfma_f32_16x16x32_bf16 v[86:89], v[172:175], v[204:207], 0
	v_mfma_f32_16x16x32_bf16 v[82:85], v[180:183], v[204:207], 0
	v_mfma_f32_16x16x32_bf16 v[70:73], v[172:175], v[212:215], 0
	v_mfma_f32_16x16x32_bf16 v[66:69], v[180:183], v[212:215], 0
	v_mfma_f32_16x16x32_bf16 v[118:121], v[176:179], v[192:195], v[118:121]
	v_mfma_f32_16x16x32_bf16 v[114:117], v[184:187], v[192:195], v[114:117]
	v_mfma_f32_16x16x32_bf16 v[102:105], v[176:179], v[200:203], v[102:105]
	v_mfma_f32_16x16x32_bf16 v[98:101], v[184:187], v[200:203], v[98:101]
	v_mfma_f32_16x16x32_bf16 v[86:89], v[176:179], v[208:211], v[86:89]
	v_mfma_f32_16x16x32_bf16 v[82:85], v[184:187], v[208:211], v[82:85]
	v_mfma_f32_16x16x32_bf16 v[70:73], v[176:179], v[216:219], v[70:73]
	v_mfma_f32_16x16x32_bf16 v[66:69], v[184:187], v[216:219], v[66:69]
	s_setprio 0
	s_barrier
	s_add_u32 s98, s38, s8
	s_addc_u32 s99, s39, s9
	s_add_u32 s100, s40, s10
	s_addc_u32 s101, s41, s11
	s_add_i32 s12, s51, s6
	s_mov_b32 m0, s12
	ds_read_b128 v[188:191], v157 offset:16384
	ds_read_b128 v[192:195], v157 offset:17408
	ds_read_b128 v[196:199], v157 offset:18432
	ds_read_b128 v[200:203], v157 offset:19456
	ds_read_b128 v[204:207], v157 offset:20480
	ds_read_b128 v[208:211], v157 offset:21504
	ds_read_b128 v[212:215], v157 offset:22528
	ds_read_b128 v[216:219], v157 offset:23552
	global_load_lds_dwordx4 v134, s[38:39]
	s_add_i32 m0, s12, 0x2000
	s_add_u32 s12, s38, 0x40000
	s_addc_u32 s13, s39, 0
	s_add_i32 s60, s52, s6
	global_load_lds_dwordx4 v130, s[38:39]
	s_mov_b32 m0, s60
	s_nop 0
	global_load_lds_dwordx4 v134, s[12:13]
	s_add_i32 m0, s60, 0x2000
	s_nop 0
	global_load_lds_dwordx4 v130, s[12:13]
	s_waitcnt vmcnt(6)
	s_waitcnt lgkmcnt(0)
	s_barrier
; #define PG8_STAGE(bufoff, gbase, voff) do { _Pragma("unroll") for (int _i = 0; _i < 2; ++_i) \
;         __builtin_amdgcn_global_load_lds((const unsigned*)((const char*)(gbase) + (voff)[_i]), (LAS unsigned*)(lds + (bufoff) + ldsw + _i * 8192), 16, 0, 0); } while (0)
; #define PG8_LDA(dst, b, h) do { _Pragma("unroll") for (int m = 0; m < 4; ++m) _Pragma("unroll") for (int k = 0; k < 2; ++k) dst[m][k] = *(const LAS bf16x8*)(lds + PG8_SA(b, h) + aoff + m * 2048 + k * 1024); } while (0)
; #define PG8_LDB(dst, b, h) do { _Pragma("unroll") for (int n = 0; n < 2; ++n) _Pragma("unroll") for (int k = 0; k < 2; ++k) dst[n][k] = *(const LAS bf16x8*)(lds + PG8_SB(b, h) + boff + n * 2048 + k * 1024); } while (0)
; #define PG8_MMA(ai, bj, At, Bt) do { __builtin_amdgcn_s_setprio(1); _Pragma("unroll") for (int m = 0; m < 4; ++m) _Pragma("unroll") for (int n = 0; n < 2; ++n) _Pragma("unroll") for (int k = 0; k < 2; ++k) \
;         acc[ai][bj][m][n] = __builtin_amdgcn_mfma_f32_16x16x32_bf16(Bt[n][k], At[m][k], acc[ai][bj][m][n], 0, 0, 0); __builtin_amdgcn_s_setprio(0); } while (0)
; #define PG8_WAIT_V(n) asm volatile("s_waitcnt vmcnt(" #n ")" ::: "memory")
; #define PG8_WAIT_L(n) asm volatile("s_waitcnt lgkmcnt(" #n ")" ::: "memory")
; #define PG8_BAR __builtin_amdgcn_s_barrier()
; #define PG8_SCHED __builtin_amdgcn_sched_barrier(0)
; template <class Epi, bool ALIGN_EPI, bool SPLITA>
; __device__ __forceinline__ void gemm_phase(LAS unsigned char* lds, const Gemm g, const StaticOrder& S, const Epi& E) {
;     ...
;             PG8_WAIT_V(8); PG8_WAIT_L(0); PG8_BAR; PG8_MMA(1, 0, At, B0); PG8_MMA(1, 1, At, B1); PG8_BAR; PG8_SCHED;
;             PG8_LDB(B0, 1, 0); PG8_LDB(B1, 1, 1); PG8_SCHED; PG8_LDA(At, 1, 0); PG8_STAGE(PG8_SA(0, 1), a2h, vo2);
;             PG8_WAIT_V(8); PG8_WAIT_L(0); PG8_BAR; PG8_MMA(0, 0, At, B0); PG8_MMA(0, 1, At, B1); PG8_BAR; PG8_SCHED;
	s_setprio 1
	s_waitcnt lgkmcnt(0)
	v_mfma_f32_16x16x32_bf16 v[62:65], v[150:153], v[188:191], 0
	v_mfma_f32_16x16x32_bf16 v[58:61], v[164:167], v[188:191], 0
	v_mfma_f32_16x16x32_bf16 v[38:41], v[150:153], v[196:199], 0
	v_mfma_f32_16x16x32_bf16 v[34:37], v[164:167], v[196:199], 0
	v_mfma_f32_16x16x32_bf16 v[22:25], v[150:153], v[204:207], 0
	v_mfma_f32_16x16x32_bf16 v[18:21], v[164:167], v[204:207], 0
	v_mfma_f32_16x16x32_bf16 v[6:9], v[150:153], v[212:215], 0
	v_mfma_f32_16x16x32_bf16 v[2:5], v[164:167], v[212:215], 0
	v_mfma_f32_16x16x32_bf16 v[62:65], v[160:163], v[192:195], v[62:65]
	v_mfma_f32_16x16x32_bf16 v[58:61], v[168:171], v[192:195], v[58:61]
	v_mfma_f32_16x16x32_bf16 v[38:41], v[160:163], v[200:203], v[38:41]
	v_mfma_f32_16x16x32_bf16 v[34:37], v[168:171], v[200:203], v[34:37]
	v_mfma_f32_16x16x32_bf16 v[22:25], v[160:163], v[208:211], v[22:25]
	v_mfma_f32_16x16x32_bf16 v[18:21], v[168:171], v[208:211], v[18:21]
	v_mfma_f32_16x16x32_bf16 v[6:9], v[160:163], v[216:219], v[6:9]
	v_mfma_f32_16x16x32_bf16 v[2:5], v[168:171], v[216:219], v[2:5]
	s_setprio 0
	s_setprio 1
	v_mfma_f32_16x16x32_bf16 v[54:57], v[172:175], v[188:191], 0
	v_mfma_f32_16x16x32_bf16 v[50:53], v[180:183], v[188:191], 0
	v_mfma_f32_16x16x32_bf16 v[42:45], v[172:175], v[196:199], 0
	v_mfma_f32_16x16x32_bf16 v[46:49], v[180:183], v[196:199], 0
	v_mfma_f32_16x16x32_bf16 v[26:29], v[172:175], v[204:207], 0
	v_mfma_f32_16x16x32_bf16 v[30:33], v[180:183], v[204:207], 0
	v_mfma_f32_16x16x32_bf16 v[10:13], v[172:175], v[212:215], 0
	v_mfma_f32_16x16x32_bf16 v[14:17], v[180:183], v[212:215], 0
	v_mfma_f32_16x16x32_bf16 v[54:57], v[176:179], v[192:195], v[54:57]
	v_mfma_f32_16x16x32_bf16 v[50:53], v[184:187], v[192:195], v[50:53]
	v_mfma_f32_16x16x32_bf16 v[42:45], v[176:179], v[200:203], v[42:45]
	v_mfma_f32_16x16x32_bf16 v[46:49], v[184:187], v[200:203], v[46:49]
	v_mfma_f32_16x16x32_bf16 v[26:29], v[176:179], v[208:211], v[26:29]
	v_mfma_f32_16x16x32_bf16 v[30:33], v[184:187], v[208:211], v[30:33]
	v_mfma_f32_16x16x32_bf16 v[10:13], v[176:179], v[216:219], v[10:13]
	v_mfma_f32_16x16x32_bf16 v[14:17], v[184:187], v[216:219], v[14:17]
	s_setprio 0
	s_barrier
	s_add_i32 s60, 0, 0x18000
	v_add_u32_e32 v149, s60, v154
	s_add_i32 s61, 0, 0x1c000
	ds_read_b128 v[150:153], v149
	ds_read_b128 v[160:163], v149 offset:1024
	ds_read_b128 v[164:167], v149 offset:2048
	ds_read_b128 v[168:171], v149 offset:3072
	v_add_u32_e32 v149, s61, v154
	ds_read_b128 v[172:175], v149
	ds_read_b128 v[176:179], v149 offset:1024
	ds_read_b128 v[180:183], v149 offset:2048
	ds_read_b128 v[184:187], v149 offset:3072
	s_add_u32 s12, s40, 0x40000
	s_addc_u32 s13, s41, 0
	s_mov_b32 m0, s42
	ds_read_b128 v[188:191], v157 offset:32768
	ds_read_b128 v[192:195], v157 offset:33792
	ds_read_b128 v[196:199], v157 offset:34816
	ds_read_b128 v[200:203], v157 offset:35840
	ds_read_b128 v[204:207], v157 offset:36864
	ds_read_b128 v[208:211], v157 offset:37888
	ds_read_b128 v[212:215], v157 offset:38912
	ds_read_b128 v[216:219], v157 offset:39936
	global_load_lds_dwordx4 v136, s[40:41]
	s_mov_b32 m0, s43
	s_nop 0
	global_load_lds_dwordx4 v132, s[40:41]
	s_mov_b32 m0, s44
	s_nop 0
	global_load_lds_dwordx4 v136, s[12:13]
	s_mov_b32 m0, s45
	s_nop 0
	global_load_lds_dwordx4 v132, s[12:13]
	s_waitcnt vmcnt(8)
	s_waitcnt lgkmcnt(0)
	s_barrier
	s_setprio 1
	s_waitcnt lgkmcnt(0)
	v_mfma_f32_16x16x32_bf16 v[126:129], v[150:153], v[188:191], v[126:129]
	v_mfma_f32_16x16x32_bf16 v[122:125], v[164:167], v[188:191], v[122:125]
	v_mfma_f32_16x16x32_bf16 v[110:113], v[150:153], v[196:199], v[110:113]
	v_mfma_f32_16x16x32_bf16 v[106:109], v[164:167], v[196:199], v[106:109]
	v_mfma_f32_16x16x32_bf16 v[94:97], v[150:153], v[204:207], v[94:97]
	v_mfma_f32_16x16x32_bf16 v[90:93], v[164:167], v[204:207], v[90:93]
	v_mfma_f32_16x16x32_bf16 v[78:81], v[150:153], v[212:215], v[78:81]
	v_mfma_f32_16x16x32_bf16 v[74:77], v[164:167], v[212:215], v[74:77]
	v_mfma_f32_16x16x32_bf16 v[126:129], v[160:163], v[192:195], v[126:129]
	v_mfma_f32_16x16x32_bf16 v[122:125], v[168:171], v[192:195], v[122:125]
	v_mfma_f32_16x16x32_bf16 v[110:113], v[160:163], v[200:203], v[110:113]
	v_mfma_f32_16x16x32_bf16 v[106:109], v[168:171], v[200:203], v[106:109]
	v_mfma_f32_16x16x32_bf16 v[94:97], v[160:163], v[208:211], v[94:97]
	v_mfma_f32_16x16x32_bf16 v[90:93], v[168:171], v[208:211], v[90:93]
	v_mfma_f32_16x16x32_bf16 v[78:81], v[160:163], v[216:219], v[78:81]
	v_mfma_f32_16x16x32_bf16 v[74:77], v[168:171], v[216:219], v[74:77]
	s_setprio 0
	s_setprio 1
	v_mfma_f32_16x16x32_bf16 v[118:121], v[172:175], v[188:191], v[118:121]
	v_mfma_f32_16x16x32_bf16 v[114:117], v[180:183], v[188:191], v[114:117]
	v_mfma_f32_16x16x32_bf16 v[102:105], v[172:175], v[196:199], v[102:105]
	v_mfma_f32_16x16x32_bf16 v[98:101], v[180:183], v[196:199], v[98:101]
	v_mfma_f32_16x16x32_bf16 v[86:89], v[172:175], v[204:207], v[86:89]
	v_mfma_f32_16x16x32_bf16 v[82:85], v[180:183], v[204:207], v[82:85]
	v_mfma_f32_16x16x32_bf16 v[70:73], v[172:175], v[212:215], v[70:73]
	v_mfma_f32_16x16x32_bf16 v[66:69], v[180:183], v[212:215], v[66:69]
	v_mfma_f32_16x16x32_bf16 v[118:121], v[176:179], v[192:195], v[118:121]
	v_mfma_f32_16x16x32_bf16 v[114:117], v[184:187], v[192:195], v[114:117]
	v_mfma_f32_16x16x32_bf16 v[102:105], v[176:179], v[200:203], v[102:105]
	v_mfma_f32_16x16x32_bf16 v[98:101], v[184:187], v[200:203], v[98:101]
	v_mfma_f32_16x16x32_bf16 v[86:89], v[176:179], v[208:211], v[86:89]
	v_mfma_f32_16x16x32_bf16 v[82:85], v[184:187], v[208:211], v[82:85]
	v_mfma_f32_16x16x32_bf16 v[70:73], v[176:179], v[216:219], v[70:73]
	v_mfma_f32_16x16x32_bf16 v[66:69], v[184:187], v[216:219], v[66:69]
	s_setprio 0
	s_barrier
; #define PG8_STAGE(bufoff, gbase, voff) do { _Pragma("unroll") for (int _i = 0; _i < 2; ++_i) \
;         __builtin_amdgcn_global_load_lds((const unsigned*)((const char*)(gbase) + (voff)[_i]), (LAS unsigned*)(lds + (bufoff) + ldsw + _i * 8192), 16, 0, 0); } while (0)
; #define PG8_WAIT_V(n) asm volatile("s_waitcnt vmcnt(" #n ")" ::: "memory")
; template <class Epi, bool ALIGN_EPI, bool SPLITA>
; __device__ __forceinline__ void gemm_phase(LAS unsigned char* lds, const Gemm g, const StaticOrder& S, const Epi& E) {
;     ...
;         for (int t = 0; t < nt; t += 2) {
;             const bool last = (t == nt - 2);
;             if constexpr (Epi::MIDK) { if (t == g.ksplit) E.mid(acc, cur, wr, wc, fr, fq); }
;             const char *a1, *a2;
;             if constexpr (SPLITA) {
;                 a1 = (t + 1 < g.ksplit) ? cA + (size_t)(t + 1) * kstep : cA2 + (size_t)(t + 1 - g.ksplit) * 2048;
;                 a2 = last ? nA : ((t + 2 < g.ksplit) ? cA + (size_t)(t + 2) * kstep : cA2 + (size_t)(t + 2 - g.ksplit) * 2048);
;             } else { a1 = cA + kofs(t + 1); a2 = last ? nA : cA + kofs(t + 2); }
;             const char* b2 = last ? nB : cB + (size_t)(t + 2) * kstepB;
;             const bool s2a = SPLITA && (t + 1 >= g.ksplit), s2b = SPLITA && !last && (t + 2 >= g.ksplit);
;             const char* a3 = a2 + ((Epi::KSUB || s2b) ? (size_t)2048 : kstep); const char* b3 = b2 + kstepB;
;             const bool m1 = SPLITA && mirC && (t + 1 < g.ksplit), m2 = SPLITA && (last ? mirN : (mirC && (t + 2 < g.ksplit)));
;             const unsigned vo1[2] = {s2a ? voffA2[0] : m1 ? voffAm[0] : voffA[0], s2a ? voffA2[1] : m1 ? voffAm[1] : voffA[1]}, vo2[2] = {s2b ? voffA2[0] : m2 ? voffAm[0] : voffA[0], s2b ? voffA2[1] : m2 ? voffAm[1] : voffA[1]};
;             const char* a1h = m1 ? a1 - hstepA : a1 + hstepA; const char* a2h = m2 ? a2 - hstepA : a2 + hstepA;
;             PG8_LDB(B0, 0, 0); PG8_LDB(B1, 0, 1); PG8_SCHED; PG8_LDA(At, 0, 0); PG8_STAGE(PG8_SA(1, 1), a1h, vo1);
;             PG8_WAIT_V(8); PG8_WAIT_L(0); PG8_BAR; PG8_MMA(0, 0, At, B0); PG8_MMA(0, 1, At, B1); PG8_BAR; PG8_SCHED;
;     ...
;             PG8_LDA(At, 1, 1); PG8_STAGE(PG8_SB(1, 0), b3, voffB); PG8_STAGE(PG8_SB(1, 1), b3 + hstepB, voffB); PG8_STAGE(PG8_SA(1, 0), a3, vo2);
;             PG8_WAIT_V(8); PG8_WAIT_L(0); PG8_BAR; PG8_MMA(1, 0, At, B0); PG8_MMA(1, 1, At, B1); PG8_BAR; PG8_SCHED;
	s_add_i32 s12, s60, s6
	s_mov_b32 m0, s12
	ds_read_b128 v[188:191], v157 offset:49152
	ds_read_b128 v[192:195], v157 offset:50176
	ds_read_b128 v[196:199], v157 offset:51200
	ds_read_b128 v[200:203], v157 offset:52224
	ds_read_b128 v[204:207], v157 offset:53248
	ds_read_b128 v[208:211], v157 offset:54272
	ds_read_b128 v[212:215], v157 offset:55296
	ds_read_b128 v[216:219], v157 offset:56320
	global_load_lds_dwordx4 v134, s[98:99]
	s_add_i32 m0, s12, 0x2000
	s_add_u32 s12, s38, 0x40800
	s_addc_u32 s13, s39, 0
	s_add_i32 s38, s61, s6
	global_load_lds_dwordx4 v130, s[98:99]
	s_mov_b32 m0, s38
	s_nop 0
	global_load_lds_dwordx4 v134, s[12:13]
	s_add_i32 m0, s38, 0x2000
	s_nop 0
	global_load_lds_dwordx4 v130, s[12:13]
	s_waitcnt vmcnt(6)
	s_waitcnt lgkmcnt(0)
	s_barrier
	s_setprio 1
	s_waitcnt lgkmcnt(0)
	v_mfma_f32_16x16x32_bf16 v[62:65], v[150:153], v[188:191], v[62:65]
	v_mfma_f32_16x16x32_bf16 v[58:61], v[164:167], v[188:191], v[58:61]
	v_mfma_f32_16x16x32_bf16 v[38:41], v[150:153], v[196:199], v[38:41]
	v_mfma_f32_16x16x32_bf16 v[34:37], v[164:167], v[196:199], v[34:37]
	v_mfma_f32_16x16x32_bf16 v[22:25], v[150:153], v[204:207], v[22:25]
	v_mfma_f32_16x16x32_bf16 v[18:21], v[164:167], v[204:207], v[18:21]
	v_mfma_f32_16x16x32_bf16 v[6:9], v[150:153], v[212:215], v[6:9]
	v_mfma_f32_16x16x32_bf16 v[2:5], v[164:167], v[212:215], v[2:5]
	v_mfma_f32_16x16x32_bf16 v[62:65], v[160:163], v[192:195], v[62:65]
	v_mfma_f32_16x16x32_bf16 v[58:61], v[168:171], v[192:195], v[58:61]
	v_mfma_f32_16x16x32_bf16 v[38:41], v[160:163], v[200:203], v[38:41]
	v_mfma_f32_16x16x32_bf16 v[34:37], v[168:171], v[200:203], v[34:37]
	v_mfma_f32_16x16x32_bf16 v[22:25], v[160:163], v[208:211], v[22:25]
	v_mfma_f32_16x16x32_bf16 v[18:21], v[168:171], v[208:211], v[18:21]
	v_mfma_f32_16x16x32_bf16 v[6:9], v[160:163], v[216:219], v[6:9]
	v_mfma_f32_16x16x32_bf16 v[2:5], v[168:171], v[216:219], v[2:5]
	s_setprio 0
	s_setprio 1
	v_mfma_f32_16x16x32_bf16 v[54:57], v[172:175], v[188:191], v[54:57]
	v_mfma_f32_16x16x32_bf16 v[50:53], v[180:183], v[188:191], v[50:53]
	v_mfma_f32_16x16x32_bf16 v[42:45], v[172:175], v[196:199], v[42:45]
	v_mfma_f32_16x16x32_bf16 v[46:49], v[180:183], v[196:199], v[46:49]
	v_mfma_f32_16x16x32_bf16 v[26:29], v[172:175], v[204:207], v[26:29]
	v_mfma_f32_16x16x32_bf16 v[30:33], v[180:183], v[204:207], v[30:33]
	v_mfma_f32_16x16x32_bf16 v[10:13], v[172:175], v[212:215], v[10:13]
	v_mfma_f32_16x16x32_bf16 v[14:17], v[180:183], v[212:215], v[14:17]
	v_mfma_f32_16x16x32_bf16 v[54:57], v[176:179], v[192:195], v[54:57]
	v_mfma_f32_16x16x32_bf16 v[50:53], v[184:187], v[192:195], v[50:53]
	v_mfma_f32_16x16x32_bf16 v[42:45], v[176:179], v[200:203], v[42:45]
	v_mfma_f32_16x16x32_bf16 v[46:49], v[184:187], v[200:203], v[46:49]
	v_mfma_f32_16x16x32_bf16 v[26:29], v[176:179], v[208:211], v[26:29]
	v_mfma_f32_16x16x32_bf16 v[30:33], v[184:187], v[208:211], v[30:33]
	v_mfma_f32_16x16x32_bf16 v[10:13], v[176:179], v[216:219], v[10:13]
	v_mfma_f32_16x16x32_bf16 v[14:17], v[184:187], v[216:219], v[14:17]
	s_setprio 0
	s_barrier
	s_add_i32 s57, s57, 2
	s_add_u32 s55, s55, 0x1000
	s_addc_u32 s56, s56, 0
	s_add_u32 s36, s36, 0x100
	s_addc_u32 s37, s37, 0
.LBB0_796:
	ds_read_b128 v[150:153], v155
	ds_read_b128 v[160:163], v155 offset:1024
	ds_read_b128 v[164:167], v155 offset:2048
	ds_read_b128 v[168:171], v155 offset:3072
	ds_read_b128 v[172:175], v156
	ds_read_b128 v[176:179], v156 offset:1024
	ds_read_b128 v[180:183], v156 offset:2048
	ds_read_b128 v[184:187], v156 offset:3072
	s_add_u32 s98, s36, 0xfffc0000
	s_addc_u32 s99, s37, -1
	s_add_u32 s12, s36, 0xfffc0080
	s_addc_u32 s13, s37, -1
	s_cmp_eq_u32 s57, 12
	s_cselect_b32 s41, s19, s13
	s_cselect_b32 s40, s29, s12
	s_cselect_b32 s39, s21, s56
	s_cselect_b32 s38, s31, s55
	s_mov_b32 m0, s49
	ds_read_b128 v[188:191], v157
	ds_read_b128 v[192:195], v157 offset:1024
	ds_read_b128 v[196:199], v157 offset:2048
	ds_read_b128 v[200:203], v157 offset:3072
	ds_read_b128 v[204:207], v157 offset:4096
	ds_read_b128 v[208:211], v157 offset:5120
	ds_read_b128 v[212:215], v157 offset:6144
	ds_read_b128 v[216:219], v157 offset:7168
	global_load_lds_dwordx4 v136, s[98:99]
	s_mov_b32 m0, s50
	s_nop 0
	global_load_lds_dwordx4 v132, s[98:99]
	s_add_i32 m0, s42, 0xc000
	s_nop 0
	global_load_lds_dwordx4 v140, s[36:37]
	s_add_i32 m0, s42, 0xe000
	s_nop 0
	global_load_lds_dwordx4 v142, s[36:37]
	s_waitcnt vmcnt(8)
	s_waitcnt lgkmcnt(0)
	s_barrier
	s_setprio 1
	s_waitcnt lgkmcnt(0)
	v_mfma_f32_16x16x32_bf16 v[126:129], v[150:153], v[188:191], v[126:129]
	v_mfma_f32_16x16x32_bf16 v[122:125], v[164:167], v[188:191], v[122:125]
	v_mfma_f32_16x16x32_bf16 v[110:113], v[150:153], v[196:199], v[110:113]
	v_mfma_f32_16x16x32_bf16 v[106:109], v[164:167], v[196:199], v[106:109]
	v_mfma_f32_16x16x32_bf16 v[94:97], v[150:153], v[204:207], v[94:97]
	v_mfma_f32_16x16x32_bf16 v[90:93], v[164:167], v[204:207], v[90:93]
	v_mfma_f32_16x16x32_bf16 v[78:81], v[150:153], v[212:215], v[78:81]
	v_mfma_f32_16x16x32_bf16 v[74:77], v[164:167], v[212:215], v[74:77]
	v_mfma_f32_16x16x32_bf16 v[126:129], v[160:163], v[192:195], v[126:129]
	v_mfma_f32_16x16x32_bf16 v[122:125], v[168:171], v[192:195], v[122:125]
	v_mfma_f32_16x16x32_bf16 v[110:113], v[160:163], v[200:203], v[110:113]
	v_mfma_f32_16x16x32_bf16 v[106:109], v[168:171], v[200:203], v[106:109]
	v_mfma_f32_16x16x32_bf16 v[94:97], v[160:163], v[208:211], v[94:97]
	v_mfma_f32_16x16x32_bf16 v[90:93], v[168:171], v[208:211], v[90:93]
	v_mfma_f32_16x16x32_bf16 v[78:81], v[160:163], v[216:219], v[78:81]
	v_mfma_f32_16x16x32_bf16 v[74:77], v[168:171], v[216:219], v[74:77]
	s_setprio 0
	s_setprio 1
	v_mfma_f32_16x16x32_bf16 v[118:121], v[172:175], v[188:191], v[118:121]
	v_mfma_f32_16x16x32_bf16 v[114:117], v[180:183], v[188:191], v[114:117]
	v_mfma_f32_16x16x32_bf16 v[102:105], v[172:175], v[196:199], v[102:105]
	v_mfma_f32_16x16x32_bf16 v[98:101], v[180:183], v[196:199], v[98:101]
	v_mfma_f32_16x16x32_bf16 v[86:89], v[172:175], v[204:207], v[86:89]
	v_mfma_f32_16x16x32_bf16 v[82:85], v[180:183], v[204:207], v[82:85]
	v_mfma_f32_16x16x32_bf16 v[70:73], v[172:175], v[212:215], v[70:73]
	v_mfma_f32_16x16x32_bf16 v[66:69], v[180:183], v[212:215], v[66:69]
	v_mfma_f32_16x16x32_bf16 v[118:121], v[176:179], v[192:195], v[118:121]
	v_mfma_f32_16x16x32_bf16 v[114:117], v[184:187], v[192:195], v[114:117]
	v_mfma_f32_16x16x32_bf16 v[102:105], v[176:179], v[200:203], v[102:105]
	v_mfma_f32_16x16x32_bf16 v[98:101], v[184:187], v[200:203], v[98:101]
	v_mfma_f32_16x16x32_bf16 v[86:89], v[176:179], v[208:211], v[86:89]
	v_mfma_f32_16x16x32_bf16 v[82:85], v[184:187], v[208:211], v[82:85]
	v_mfma_f32_16x16x32_bf16 v[70:73], v[176:179], v[216:219], v[70:73]
	v_mfma_f32_16x16x32_bf16 v[66:69], v[184:187], v[216:219], v[66:69]
	s_setprio 0
	s_barrier
; #define PG8_STAGE(bufoff, gbase, voff) do { _Pragma("unroll") for (int _i = 0; _i < 2; ++_i) \
;         __builtin_amdgcn_global_load_lds((const unsigned*)((const char*)(gbase) + (voff)[_i]), (LAS unsigned*)(lds + (bufoff) + ldsw + _i * 8192), 16, 0, 0); } while (0)
; #define PG8_LDA(dst, b, h) do { _Pragma("unroll") for (int m = 0; m < 4; ++m) _Pragma("unroll") for (int k = 0; k < 2; ++k) dst[m][k] = *(const LAS bf16x8*)(lds + PG8_SA(b, h) + aoff + m * 2048 + k * 1024); } while (0)
; #define PG8_LDB(dst, b, h) do { _Pragma("unroll") for (int n = 0; n < 2; ++n) _Pragma("unroll") for (int k = 0; k < 2; ++k) dst[n][k] = *(const LAS bf16x8*)(lds + PG8_SB(b, h) + boff + n * 2048 + k * 1024); } while (0)
; #define PG8_MMA(ai, bj, At, Bt) do { __builtin_amdgcn_s_setprio(1); _Pragma("unroll") for (int m = 0; m < 4; ++m) _Pragma("unroll") for (int n = 0; n < 2; ++n) _Pragma("unroll") for (int k = 0; k < 2; ++k) \
;         acc[ai][bj][m][n] = __builtin_amdgcn_mfma_f32_16x16x32_bf16(Bt[n][k], At[m][k], acc[ai][bj][m][n], 0, 0, 0); __builtin_amdgcn_s_setprio(0); } while (0)
; #define PG8_WAIT_V(n) asm volatile("s_waitcnt vmcnt(" #n ")" ::: "memory")
; #define PG8_WAIT_L(n) asm volatile("s_waitcnt lgkmcnt(" #n ")" ::: "memory")
; #define PG8_BAR __builtin_amdgcn_s_barrier()
; #define PG8_SCHED __builtin_amdgcn_sched_barrier(0)
; template <class Epi, bool ALIGN_EPI, bool SPLITA>
; __device__ __forceinline__ void gemm_phase(LAS unsigned char* lds, const Gemm g, const StaticOrder& S, const Epi& E) {
;     ...
;             PG8_LDA(At, 0, 1); PG8_STAGE(PG8_SB(0, 0), b2, voffB); PG8_STAGE(PG8_SB(0, 1), b2 + hstepB, voffB); PG8_STAGE(PG8_SA(0, 0), a2, vo2);
;             PG8_WAIT_V(8); PG8_WAIT_L(0); PG8_BAR; PG8_MMA(1, 0, At, B0); PG8_MMA(1, 1, At, B1); PG8_BAR; PG8_SCHED;
;             PG8_LDB(B0, 1, 0); PG8_LDB(B1, 1, 1); PG8_SCHED; PG8_LDA(At, 1, 0); PG8_STAGE(PG8_SA(0, 1), a2h, vo2);
;             PG8_WAIT_V(8); PG8_WAIT_L(0); PG8_BAR; PG8_MMA(0, 0, At, B0); PG8_MMA(0, 1, At, B1); PG8_BAR; PG8_SCHED;
;             PG8_LDA(At, 1, 1); PG8_STAGE(PG8_SB(1, 0), b3, voffB); PG8_STAGE(PG8_SB(1, 1), b3 + hstepB, voffB); PG8_STAGE(PG8_SA(1, 0), a3, vo2);
	s_add_u32 s98, s38, s8
	s_addc_u32 s99, s39, s9
	s_add_u32 s100, s40, s10
	s_addc_u32 s101, s41, s11
	s_add_i32 s12, s51, s6
	s_mov_b32 m0, s12
	ds_read_b128 v[188:191], v157 offset:16384
	ds_read_b128 v[192:195], v157 offset:17408
	ds_read_b128 v[196:199], v157 offset:18432
	ds_read_b128 v[200:203], v157 offset:19456
	ds_read_b128 v[204:207], v157 offset:20480
	ds_read_b128 v[208:211], v157 offset:21504
	ds_read_b128 v[212:215], v157 offset:22528
	ds_read_b128 v[216:219], v157 offset:23552
	global_load_lds_dwordx4 v134, s[38:39]
	s_add_i32 m0, s12, 0x2000
	s_add_u32 s12, s38, 0x40000
	s_addc_u32 s13, s39, 0
	s_add_i32 s60, s52, s6
	global_load_lds_dwordx4 v130, s[38:39]
	s_mov_b32 m0, s60
	s_nop 0
	global_load_lds_dwordx4 v134, s[12:13]
	s_add_i32 m0, s60, 0x2000
	s_nop 0
	global_load_lds_dwordx4 v130, s[12:13]
	s_waitcnt vmcnt(6)
	s_waitcnt lgkmcnt(0)
	s_barrier
	s_setprio 1
	s_waitcnt lgkmcnt(0)
	v_mfma_f32_16x16x32_bf16 v[62:65], v[150:153], v[188:191], v[62:65]
	v_mfma_f32_16x16x32_bf16 v[58:61], v[164:167], v[188:191], v[58:61]
	v_mfma_f32_16x16x32_bf16 v[38:41], v[150:153], v[196:199], v[38:41]
	v_mfma_f32_16x16x32_bf16 v[34:37], v[164:167], v[196:199], v[34:37]
	v_mfma_f32_16x16x32_bf16 v[22:25], v[150:153], v[204:207], v[22:25]
	v_mfma_f32_16x16x32_bf16 v[18:21], v[164:167], v[204:207], v[18:21]
	v_mfma_f32_16x16x32_bf16 v[6:9], v[150:153], v[212:215], v[6:9]
	v_mfma_f32_16x16x32_bf16 v[2:5], v[164:167], v[212:215], v[2:5]
	v_mfma_f32_16x16x32_bf16 v[62:65], v[160:163], v[192:195], v[62:65]
	v_mfma_f32_16x16x32_bf16 v[58:61], v[168:171], v[192:195], v[58:61]
	v_mfma_f32_16x16x32_bf16 v[38:41], v[160:163], v[200:203], v[38:41]
	v_mfma_f32_16x16x32_bf16 v[34:37], v[168:171], v[200:203], v[34:37]
	v_mfma_f32_16x16x32_bf16 v[22:25], v[160:163], v[208:211], v[22:25]
	v_mfma_f32_16x16x32_bf16 v[18:21], v[168:171], v[208:211], v[18:21]
	v_mfma_f32_16x16x32_bf16 v[6:9], v[160:163], v[216:219], v[6:9]
	v_mfma_f32_16x16x32_bf16 v[2:5], v[168:171], v[216:219], v[2:5]
	s_setprio 0
	s_setprio 1
	v_mfma_f32_16x16x32_bf16 v[54:57], v[172:175], v[188:191], v[54:57]
	v_mfma_f32_16x16x32_bf16 v[50:53], v[180:183], v[188:191], v[50:53]
	v_mfma_f32_16x16x32_bf16 v[42:45], v[172:175], v[196:199], v[42:45]
	v_mfma_f32_16x16x32_bf16 v[46:49], v[180:183], v[196:199], v[46:49]
	v_mfma_f32_16x16x32_bf16 v[26:29], v[172:175], v[204:207], v[26:29]
	v_mfma_f32_16x16x32_bf16 v[30:33], v[180:183], v[204:207], v[30:33]
	v_mfma_f32_16x16x32_bf16 v[10:13], v[172:175], v[212:215], v[10:13]
	v_mfma_f32_16x16x32_bf16 v[14:17], v[180:183], v[212:215], v[14:17]
	v_mfma_f32_16x16x32_bf16 v[54:57], v[176:179], v[192:195], v[54:57]
	v_mfma_f32_16x16x32_bf16 v[50:53], v[184:187], v[192:195], v[50:53]
	v_mfma_f32_16x16x32_bf16 v[42:45], v[176:179], v[200:203], v[42:45]
	v_mfma_f32_16x16x32_bf16 v[46:49], v[184:187], v[200:203], v[46:49]
	v_mfma_f32_16x16x32_bf16 v[26:29], v[176:179], v[208:211], v[26:29]
	v_mfma_f32_16x16x32_bf16 v[30:33], v[184:187], v[208:211], v[30:33]
	v_mfma_f32_16x16x32_bf16 v[10:13], v[176:179], v[216:219], v[10:13]
	v_mfma_f32_16x16x32_bf16 v[14:17], v[184:187], v[216:219], v[14:17]
	s_setprio 0
	s_barrier
	s_add_i32 s60, 0, 0x18000
	v_add_u32_e32 v149, s60, v154
	s_add_i32 s61, 0, 0x1c000
	ds_read_b128 v[150:153], v149
	ds_read_b128 v[160:163], v149 offset:1024
	ds_read_b128 v[164:167], v149 offset:2048
	ds_read_b128 v[168:171], v149 offset:3072
	v_add_u32_e32 v149, s61, v154
	ds_read_b128 v[172:175], v149
	ds_read_b128 v[176:179], v149 offset:1024
	ds_read_b128 v[180:183], v149 offset:2048
	ds_read_b128 v[184:187], v149 offset:3072
	s_add_u32 s12, s40, 0x40000
	s_addc_u32 s13, s41, 0
	s_mov_b32 m0, s42
	ds_read_b128 v[188:191], v157 offset:32768
	ds_read_b128 v[192:195], v157 offset:33792
	ds_read_b128 v[196:199], v157 offset:34816
	ds_read_b128 v[200:203], v157 offset:35840
	ds_read_b128 v[204:207], v157 offset:36864
	ds_read_b128 v[208:211], v157 offset:37888
	ds_read_b128 v[212:215], v157 offset:38912
	ds_read_b128 v[216:219], v157 offset:39936
	global_load_lds_dwordx4 v136, s[40:41]
	s_mov_b32 m0, s43
	s_nop 0
	global_load_lds_dwordx4 v132, s[40:41]
	s_mov_b32 m0, s44
	s_nop 0
	global_load_lds_dwordx4 v136, s[12:13]
	s_mov_b32 m0, s45
	s_nop 0
	global_load_lds_dwordx4 v132, s[12:13]
	s_waitcnt vmcnt(8)
	s_waitcnt lgkmcnt(0)
	s_barrier
; #define PG8_STAGE(bufoff, gbase, voff) do { _Pragma("unroll") for (int _i = 0; _i < 2; ++_i) \
;         __builtin_amdgcn_global_load_lds((const unsigned*)((const char*)(gbase) + (voff)[_i]), (LAS unsigned*)(lds + (bufoff) + ldsw + _i * 8192), 16, 0, 0); } while (0)
; #define PG8_LDA(dst, b, h) do { _Pragma("unroll") for (int m = 0; m < 4; ++m) _Pragma("unroll") for (int k = 0; k < 2; ++k) dst[m][k] = *(const LAS bf16x8*)(lds + PG8_SA(b, h) + aoff + m * 2048 + k * 1024); } while (0)
; #define PG8_MMA(ai, bj, At, Bt) do { __builtin_amdgcn_s_setprio(1); _Pragma("unroll") for (int m = 0; m < 4; ++m) _Pragma("unroll") for (int n = 0; n < 2; ++n) _Pragma("unroll") for (int k = 0; k < 2; ++k) \
;         acc[ai][bj][m][n] = __builtin_amdgcn_mfma_f32_16x16x32_bf16(Bt[n][k], At[m][k], acc[ai][bj][m][n], 0, 0, 0); __builtin_amdgcn_s_setprio(0); } while (0)
; #define PG8_WAIT_V(n) asm volatile("s_waitcnt vmcnt(" #n ")" ::: "memory")
; #define PG8_WAIT_L(n) asm volatile("s_waitcnt lgkmcnt(" #n ")" ::: "memory")
; #define PG8_BAR __builtin_amdgcn_s_barrier()
; #define PG8_SCHED __builtin_amdgcn_sched_barrier(0)
; template <class Epi, bool ALIGN_EPI, bool SPLITA>
; __device__ __forceinline__ void gemm_phase(LAS unsigned char* lds, const Gemm g, const StaticOrder& S, const Epi& E) {
;     ...
;             PG8_WAIT_V(8); PG8_WAIT_L(0); PG8_BAR; PG8_MMA(0, 0, At, B0); PG8_MMA(0, 1, At, B1); PG8_BAR; PG8_SCHED;
;             PG8_LDA(At, 1, 1); PG8_STAGE(PG8_SB(1, 0), b3, voffB); PG8_STAGE(PG8_SB(1, 1), b3 + hstepB, voffB); PG8_STAGE(PG8_SA(1, 0), a3, vo2);
;             PG8_WAIT_V(8); PG8_WAIT_L(0); PG8_BAR; PG8_MMA(1, 0, At, B0); PG8_MMA(1, 1, At, B1); PG8_BAR; PG8_SCHED;
;         }
;         if constexpr (ALIGN_EPI) { if (wr == 0) PG8_BAR; }
	s_setprio 1
	s_waitcnt lgkmcnt(0)
	v_mfma_f32_16x16x32_bf16 v[126:129], v[150:153], v[188:191], v[126:129]
	v_mfma_f32_16x16x32_bf16 v[122:125], v[164:167], v[188:191], v[122:125]
	v_mfma_f32_16x16x32_bf16 v[110:113], v[150:153], v[196:199], v[110:113]
	v_mfma_f32_16x16x32_bf16 v[106:109], v[164:167], v[196:199], v[106:109]
	v_mfma_f32_16x16x32_bf16 v[94:97], v[150:153], v[204:207], v[94:97]
	v_mfma_f32_16x16x32_bf16 v[90:93], v[164:167], v[204:207], v[90:93]
	v_mfma_f32_16x16x32_bf16 v[78:81], v[150:153], v[212:215], v[78:81]
	v_mfma_f32_16x16x32_bf16 v[74:77], v[164:167], v[212:215], v[74:77]
	v_mfma_f32_16x16x32_bf16 v[126:129], v[160:163], v[192:195], v[126:129]
	v_mfma_f32_16x16x32_bf16 v[122:125], v[168:171], v[192:195], v[122:125]
	v_mfma_f32_16x16x32_bf16 v[110:113], v[160:163], v[200:203], v[110:113]
	v_mfma_f32_16x16x32_bf16 v[106:109], v[168:171], v[200:203], v[106:109]
	v_mfma_f32_16x16x32_bf16 v[94:97], v[160:163], v[208:211], v[94:97]
	v_mfma_f32_16x16x32_bf16 v[90:93], v[168:171], v[208:211], v[90:93]
	v_mfma_f32_16x16x32_bf16 v[78:81], v[160:163], v[216:219], v[78:81]
	v_mfma_f32_16x16x32_bf16 v[74:77], v[168:171], v[216:219], v[74:77]
	s_setprio 0
	s_setprio 1
	v_mfma_f32_16x16x32_bf16 v[118:121], v[172:175], v[188:191], v[118:121]
	v_mfma_f32_16x16x32_bf16 v[114:117], v[180:183], v[188:191], v[114:117]
	v_mfma_f32_16x16x32_bf16 v[102:105], v[172:175], v[196:199], v[102:105]
	v_mfma_f32_16x16x32_bf16 v[98:101], v[180:183], v[196:199], v[98:101]
	v_mfma_f32_16x16x32_bf16 v[86:89], v[172:175], v[204:207], v[86:89]
	v_mfma_f32_16x16x32_bf16 v[82:85], v[180:183], v[204:207], v[82:85]
	v_mfma_f32_16x16x32_bf16 v[70:73], v[172:175], v[212:215], v[70:73]
	v_mfma_f32_16x16x32_bf16 v[66:69], v[180:183], v[212:215], v[66:69]
	v_mfma_f32_16x16x32_bf16 v[118:121], v[176:179], v[192:195], v[118:121]
	v_mfma_f32_16x16x32_bf16 v[114:117], v[184:187], v[192:195], v[114:117]
	v_mfma_f32_16x16x32_bf16 v[102:105], v[176:179], v[200:203], v[102:105]
	v_mfma_f32_16x16x32_bf16 v[98:101], v[184:187], v[200:203], v[98:101]
	v_mfma_f32_16x16x32_bf16 v[86:89], v[176:179], v[208:211], v[86:89]
	v_mfma_f32_16x16x32_bf16 v[82:85], v[184:187], v[208:211], v[82:85]
	v_mfma_f32_16x16x32_bf16 v[70:73], v[176:179], v[216:219], v[70:73]
	v_mfma_f32_16x16x32_bf16 v[66:69], v[184:187], v[216:219], v[66:69]
	s_setprio 0
	s_barrier
	s_add_i32 s12, s60, s6
	s_mov_b32 m0, s12
	ds_read_b128 v[188:191], v157 offset:49152
	ds_read_b128 v[192:195], v157 offset:50176
	ds_read_b128 v[196:199], v157 offset:51200
	ds_read_b128 v[200:203], v157 offset:52224
	ds_read_b128 v[204:207], v157 offset:53248
	ds_read_b128 v[208:211], v157 offset:54272
	ds_read_b128 v[212:215], v157 offset:55296
	ds_read_b128 v[216:219], v157 offset:56320
	global_load_lds_dwordx4 v134, s[98:99]
	s_add_i32 m0, s12, 0x2000
	s_add_u32 s12, s38, 0x40800
	s_addc_u32 s13, s39, 0
	s_add_i32 s38, s61, s6
	global_load_lds_dwordx4 v130, s[98:99]
	s_mov_b32 m0, s38
	s_nop 0
	global_load_lds_dwordx4 v134, s[12:13]
	s_add_i32 m0, s38, 0x2000
	s_nop 0
	global_load_lds_dwordx4 v130, s[12:13]
	s_waitcnt vmcnt(6)
	s_waitcnt lgkmcnt(0)
	s_barrier
	s_setprio 1
	s_waitcnt lgkmcnt(0)
	v_mfma_f32_16x16x32_bf16 v[62:65], v[150:153], v[188:191], v[62:65]
	v_mfma_f32_16x16x32_bf16 v[58:61], v[164:167], v[188:191], v[58:61]
	v_mfma_f32_16x16x32_bf16 v[38:41], v[150:153], v[196:199], v[38:41]
	v_mfma_f32_16x16x32_bf16 v[34:37], v[164:167], v[196:199], v[34:37]
	v_mfma_f32_16x16x32_bf16 v[22:25], v[150:153], v[204:207], v[22:25]
	v_mfma_f32_16x16x32_bf16 v[18:21], v[164:167], v[204:207], v[18:21]
	v_mfma_f32_16x16x32_bf16 v[6:9], v[150:153], v[212:215], v[6:9]
	v_mfma_f32_16x16x32_bf16 v[2:5], v[164:167], v[212:215], v[2:5]
	v_mfma_f32_16x16x32_bf16 v[62:65], v[160:163], v[192:195], v[62:65]
	v_mfma_f32_16x16x32_bf16 v[58:61], v[168:171], v[192:195], v[58:61]
	v_mfma_f32_16x16x32_bf16 v[38:41], v[160:163], v[200:203], v[38:41]
	v_mfma_f32_16x16x32_bf16 v[34:37], v[168:171], v[200:203], v[34:37]
	v_mfma_f32_16x16x32_bf16 v[22:25], v[160:163], v[208:211], v[22:25]
	v_mfma_f32_16x16x32_bf16 v[18:21], v[168:171], v[208:211], v[18:21]
	v_mfma_f32_16x16x32_bf16 v[6:9], v[160:163], v[216:219], v[6:9]
	v_mfma_f32_16x16x32_bf16 v[2:5], v[168:171], v[216:219], v[2:5]
	s_setprio 0
	s_setprio 1
	v_mfma_f32_16x16x32_bf16 v[54:57], v[172:175], v[188:191], v[54:57]
	v_mfma_f32_16x16x32_bf16 v[50:53], v[180:183], v[188:191], v[50:53]
	v_mfma_f32_16x16x32_bf16 v[42:45], v[172:175], v[196:199], v[42:45]
	v_mfma_f32_16x16x32_bf16 v[46:49], v[180:183], v[196:199], v[46:49]
	v_mfma_f32_16x16x32_bf16 v[26:29], v[172:175], v[204:207], v[26:29]
	v_mfma_f32_16x16x32_bf16 v[30:33], v[180:183], v[204:207], v[30:33]
	v_mfma_f32_16x16x32_bf16 v[10:13], v[172:175], v[212:215], v[10:13]
	v_mfma_f32_16x16x32_bf16 v[14:17], v[180:183], v[212:215], v[14:17]
	v_mfma_f32_16x16x32_bf16 v[54:57], v[176:179], v[192:195], v[54:57]
	v_mfma_f32_16x16x32_bf16 v[50:53], v[184:187], v[192:195], v[50:53]
	v_mfma_f32_16x16x32_bf16 v[42:45], v[176:179], v[200:203], v[42:45]
	v_mfma_f32_16x16x32_bf16 v[46:49], v[184:187], v[200:203], v[46:49]
	v_mfma_f32_16x16x32_bf16 v[26:29], v[176:179], v[208:211], v[26:29]
	v_mfma_f32_16x16x32_bf16 v[30:33], v[184:187], v[208:211], v[30:33]
	v_mfma_f32_16x16x32_bf16 v[10:13], v[176:179], v[216:219], v[10:13]
	v_mfma_f32_16x16x32_bf16 v[14:17], v[184:187], v[216:219], v[14:17]
	s_setprio 0
	s_barrier
	s_add_i32 s57, s57, 2
	s_add_u32 s55, s55, 0x1000
	s_addc_u32 s56, s56, 0
	s_add_u32 s36, s36, 0x100
	s_addc_u32 s37, s37, 0
	s_cmp_gt_u32 s57, 13
	s_cbranch_scc0 .LBB0_796
	s_and_b64 vcc, exec, s[16:17]
	s_cbranch_vccz .LBB0_799
	s_barrier
